# gemm1 k-loop: LDS stores interleaved one per fragment-read batch (counted lgkmcnt), added to the other three GEMMs
# speedup vs baseline: 1.0220x; 1.0039x over previous
.LBB0_180:
	s_mov_b64 vcc, s[80:81]
	s_cbranch_vccnz .Lm1w_w0
	s_waitcnt vmcnt(8)
	s_branch .Lm1w_w1

.Lm1w_w1:
	v_add_u32_e32 v157, v137, v139
	ds_read_b128 v[198:201], v157
	v_add_u32_e32 v165, v137, v141
	ds_read_b128 v[202:205], v165 offset:16384
	ds_read_b128 v[206:209], v165 offset:20480
	ds_write_b128 v135, v[68:71] offset:32768
	v_add_u32_e32 v159, v143, v139
	v_add_u32_e32 v167, v143, v141
	v_add_u32_e32 v161, v153, v139
	v_add_u32_e32 v169, v153, v141
	v_add_u32_e32 v163, v155, v139
	s_waitcnt lgkmcnt(1)
	v_mfma_f32_32x32x16_bf16 v[48:63], v[198:201], v[202:205], v[48:63]
	v_add_u32_e32 v171, v155, v141
	s_add_i32 s21, s71, 3
	s_cmp_ge_i32 s21, s90
	v_mfma_f32_32x32x16_bf16 v[32:47], v[198:201], v[206:209], v[32:47]
	ds_read_b128 v[198:201], v157 offset:4096
	ds_write_b128 v135, v[72:75] offset:49152
	s_waitcnt lgkmcnt(1)
	v_mfma_f32_32x32x16_bf16 v[16:31], v[198:201], v[202:205], v[16:31]
	ds_read_b128 v[202:205], v167 offset:16384
	v_mfma_f32_32x32x16_bf16 v[0:15], v[198:201], v[206:209], v[0:15]
	ds_read_b128 v[198:201], v159
	ds_read_b128 v[206:209], v167 offset:20480
	ds_write_b128 v135, v[92:95] offset:36864
	s_waitcnt lgkmcnt(1)
	v_mfma_f32_32x32x16_bf16 v[48:63], v[198:201], v[202:205], v[48:63]
	v_mfma_f32_32x32x16_bf16 v[32:47], v[198:201], v[206:209], v[32:47]
	ds_read_b128 v[198:201], v159 offset:4096
	ds_write_b128 v135, v[84:87] offset:53248
	s_waitcnt lgkmcnt(1)
	v_mfma_f32_32x32x16_bf16 v[16:31], v[198:201], v[202:205], v[16:31]
	ds_read_b128 v[202:205], v169 offset:16384
	v_mfma_f32_32x32x16_bf16 v[0:15], v[198:201], v[206:209], v[0:15]
	ds_read_b128 v[198:201], v161
	ds_read_b128 v[206:209], v169 offset:20480
	ds_write_b128 v135, v[108:111] offset:40960
	s_waitcnt lgkmcnt(1)
	v_mfma_f32_32x32x16_bf16 v[48:63], v[198:201], v[202:205], v[48:63]
	v_mfma_f32_32x32x16_bf16 v[32:47], v[198:201], v[206:209], v[32:47]
	ds_read_b128 v[198:201], v161 offset:4096
	ds_write_b128 v135, v[100:103] offset:57344
	s_waitcnt lgkmcnt(1)
	v_mfma_f32_32x32x16_bf16 v[16:31], v[198:201], v[202:205], v[16:31]
	ds_read_b128 v[202:205], v171 offset:16384
	v_mfma_f32_32x32x16_bf16 v[0:15], v[198:201], v[206:209], v[0:15]
	ds_read_b128 v[198:201], v163
	ds_read_b128 v[206:209], v171 offset:20480
	ds_write_b128 v135, v[124:127] offset:45056
	s_waitcnt lgkmcnt(1)
	v_mfma_f32_32x32x16_bf16 v[48:63], v[198:201], v[202:205], v[48:63]
	v_mfma_f32_32x32x16_bf16 v[32:47], v[198:201], v[206:209], v[32:47]
	ds_read_b128 v[198:201], v163 offset:4096
	ds_write_b128 v135, v[116:119] offset:61440
	s_waitcnt lgkmcnt(1)
	v_mfma_f32_32x32x16_bf16 v[16:31], v[198:201], v[202:205], v[16:31]
	v_mfma_f32_32x32x16_bf16 v[0:15], v[198:201], v[206:209], v[0:15]
	s_waitcnt lgkmcnt(0)
	s_barrier
	s_cbranch_scc1 .LBB0_184
	s_add_i32 s21, s15, 64
	s_add_i32 s74, s15, 0x840
	s_cmp_lt_u32 s71, 13
	s_cselect_b64 s[84:85], -1, 0
	s_and_b64 vcc, s[84:85], exec
	s_cselect_b32 vcc_lo, s74, s21
	v_mov_b32_e32 v81, v80
	s_ashr_i32 vcc_hi, vcc_lo, 31
	v_mov_b32_e32 v82, v80
	v_mov_b32_e32 v83, v80
	v_mov_b64_e32 v[68:69], v[80:81]
	v_lshl_add_u64 v[116:117], vcc, 1, v[178:179]
	s_or_b64 vcc, s[84:85], s[4:5]
	v_mov_b64_e32 v[70:71], v[82:83]
	s_and_saveexec_b64 s[84:85], vcc
	s_cbranch_execz .LBB0_183
	global_load_dwordx4 v[68:71], v[116:117], off

.LBB0_184:
	s_waitcnt vmcnt(8)
	ds_read_b128 v[198:201], v157 offset:32768
	ds_read_b128 v[202:205], v165 offset:49152
	ds_read_b128 v[206:209], v165 offset:53248
	ds_write_b128 v135, v[64:67]
	s_andn2_b64 vcc, exec, s[82:83]
	s_waitcnt lgkmcnt(1)
	v_mfma_f32_32x32x16_bf16 v[48:63], v[198:201], v[202:205], v[48:63]
	v_mfma_f32_32x32x16_bf16 v[32:47], v[198:201], v[206:209], v[32:47]
	ds_read_b128 v[198:201], v157 offset:36864
	ds_write_b128 v135, v[76:79] offset:16384
	s_waitcnt lgkmcnt(1)
	v_mfma_f32_32x32x16_bf16 v[16:31], v[198:201], v[202:205], v[16:31]
	v_mfma_f32_32x32x16_bf16 v[0:15], v[198:201], v[206:209], v[0:15]
	ds_read_b128 v[198:201], v159 offset:32768
	ds_read_b128 v[202:205], v167 offset:49152
	ds_read_b128 v[206:209], v167 offset:53248
	ds_write_b128 v135, v[96:99] offset:4096
	s_waitcnt lgkmcnt(1)
	v_mfma_f32_32x32x16_bf16 v[48:63], v[198:201], v[202:205], v[48:63]
	v_mfma_f32_32x32x16_bf16 v[32:47], v[198:201], v[206:209], v[32:47]
	ds_read_b128 v[198:201], v159 offset:36864
	ds_write_b128 v135, v[88:91] offset:20480
	s_waitcnt lgkmcnt(1)
	v_mfma_f32_32x32x16_bf16 v[16:31], v[198:201], v[202:205], v[16:31]
	v_mfma_f32_32x32x16_bf16 v[0:15], v[198:201], v[206:209], v[0:15]
	ds_read_b128 v[198:201], v161 offset:32768
	ds_read_b128 v[202:205], v169 offset:49152
	ds_read_b128 v[206:209], v169 offset:53248
	ds_write_b128 v135, v[112:115] offset:8192
	s_waitcnt lgkmcnt(1)
	v_mfma_f32_32x32x16_bf16 v[48:63], v[198:201], v[202:205], v[48:63]
	v_mfma_f32_32x32x16_bf16 v[32:47], v[198:201], v[206:209], v[32:47]
	ds_read_b128 v[198:201], v161 offset:36864
	ds_write_b128 v135, v[104:107] offset:24576
	s_waitcnt lgkmcnt(1)
	v_mfma_f32_32x32x16_bf16 v[16:31], v[198:201], v[202:205], v[16:31]
	v_mfma_f32_32x32x16_bf16 v[0:15], v[198:201], v[206:209], v[0:15]
	ds_read_b128 v[198:201], v163 offset:32768
	ds_read_b128 v[202:205], v171 offset:49152
	ds_read_b128 v[206:209], v171 offset:53248
	ds_write_b128 v135, v[128:131] offset:12288
	s_waitcnt lgkmcnt(1)
	v_mfma_f32_32x32x16_bf16 v[48:63], v[198:201], v[202:205], v[48:63]
	v_mfma_f32_32x32x16_bf16 v[32:47], v[198:201], v[206:209], v[32:47]
	ds_read_b128 v[198:201], v163 offset:36864
	ds_write_b128 v135, v[120:123] offset:28672
	s_waitcnt lgkmcnt(1)
	v_mfma_f32_32x32x16_bf16 v[16:31], v[198:201], v[202:205], v[16:31]
	v_mfma_f32_32x32x16_bf16 v[0:15], v[198:201], v[206:209], v[0:15]
